# workgroup start stagger in the two big GEMM phases (w_in, gate_up): each workgroup sleeps (bid>>3)&7 microseconds after the grid barrier so the 8 groups' epilogue HBM bursts no longer coincide
# baseline (speedup 1.0000x reference)
; __global__ void __launch_bounds__(NTHR) mega(Params p) {
;     ...
;     for (int ph = p.ph_lo; ph < p.ph_hi; ++ph) {
;         if (ph == 0) { if (PHE(0)) { for (int rp = 0; rp < (PROBE_SEL == 3 ? 2 : 1); ++rp) {
;             { int t0 = threadIdx.x; asm volatile("" : "+v"(t0)); if (blockIdx.x == 0 && t0 < 64) ctr[t0] = 0u; }
;             for (int it = blockIdx.x; it < 192 + 128; it += gridDim.x) { if (it < 192) ada_item(lds, p, it); else rope_item(p, it - 192); }
;             conv_weights(lds, p, 0, 0, 6, 320); } }
;         } else if (ph == NPHASE - 1) {
;             if (PHE(10)) norm_rows<true, true>(nullptr, XA, p.final_norm, nullptr, 0, 0, nullptr, p.out);
;         } else {
;             const int l = (ph - 1) / 9, s = (ph - 1) % 9;
;             const float* modl = MOD + (size_t)l * NB * 6 * D;
;             switch (s) {
;             case 0: if (PHE(1)) { if (l > 0) conv_weights(lds, p, l, 0, 6, 0);
;                 if (l == 0) norm_rows<false, false>(p.x, nullptr, p.norm_mix + l * D, modl, 0, 1, H, nullptr);
;                 else norm_rows<false, true>(nullptr, XA, p.norm_mix + l * D, modl, 0, 1, H, nullptr); } break;
;             case 1: if (PHE(2)) { EpiIn e; e.CQ = (bf16_t*)(ws + AR_CQ); e.CKV = (bf16_t*)(ws + AR_CKV); e.QKVG = (bf16_t*)(ws + AR_QKVG); e.Z = (bf16_t*)(ws + AR_Z); e.GATE = (bf16_t*)(ws + AR_GATE);
;                 e.Kb = (bf16_t*)(ws + AR_K); e.SSQ = (float*)(ws + WS_SSQ); e.BA = (float*)(ws + WS_BA); e.COS = (const float*)(ws + WS_COS); e.SIN = (const float*)(ws + WS_SIN);
;                 pg8::gemm_phase(lds, pg8::Gemm{H, (const bf16_t*)(ws + WS_WIN), T, INWP, D}, e); } break;
.LBB0_11:
	s_lshl_b32 s98, 1, s84
	s_and_b32 s98, s98, 0x20904
	s_cbranch_scc0 .Lstag_done
	v_readlane_b32 s98, v254, 51
	s_nop 3
	s_bfe_u32 s98, s98, 0x30003
	s_cmp_eq_u32 s98, 0
	s_cbranch_scc1 .Lstag_done
.Lstag_loop:
	s_sleep 37
	s_add_i32 s98, s98, -1
	s_cmp_lg_u32 s98, 0
	s_cbranch_scc1 .Lstag_loop
